# G1 gla_prep prologue de-serialisation: four lrs loads issued together, weight loads behind them, one counted wait before the LDS staging writes
# baseline (speedup 1.0000x reference)
; __device__ __forceinline__ float bf2f(bf16_t h) { return __uint_as_float(((unsigned)h) << 16); }
; __device__ __forceinline__ void gla_prep(const Params& p, int tok0, int h, char* lds) {
;     const int tid = TIDX;
;     float* bc = (float*)lds;
;     float* lrs = (float*)(lds + 32768);
;     const bf16_t* Z = (const bf16_t*)(p.ws + OFF_Z);
;     for (int i = tid; i < 1024; i += NTHREADS) { const int t = i >> 4, rr = i & 15; lrs[i] = bf2f(Z[(size_t)(tok0 + t) * ZC + ZLR + rr]); }
;     const int d = tid & 127, th = tid >> 7;
;     float w[16];
; #pragma unroll
;     for (int rr = 0; rr < 16; rr++) w[rr] = p.gla_wa2[rr * 512 + h * 128 + d];
;     const float bias = p.gla_ba2[h * 128 + d];
;     __syncthreads();
.LBB0_379:
	s_mov_b64 s[34:35], s[80:81]
	v_mov_b32_e32 v12, v158
	s_load_dwordx4 s[4:7], s[34:35], 0xd0
	v_mov_b32_e32 v22, v158
	s_and_b32 s8, s2, 0xfffff800
	v_and_b32_e32 v0, 15, v22
	v_lshlrev_b32_e32 v8, 1, v0
	v_bfe_u32 v4, v22, 4, 4
	s_and_b32 s9, s36, 0x7c0
	v_and_b32_e32 v13, 0xff, v22
	s_waitcnt lgkmcnt(0)
	v_lshl_add_u64 v[0:1], s[6:7], 0, v[8:9]
	v_or_b32_e32 v4, s8, v4
	v_lshl_add_u64 v[0:1], v[0:1], 0, s[16:17]
	v_lshl_add_u32 v2, v13, 2, s1
	v_or_b32_e32 v3, 0xffffff00, v13
	v_or_b32_e32 v4, s9, v4
	s_mov_b64 s[8:9], 0
	v_mad_i64_i32 v[38:39], s[10:11], v4, s38, v[0:1]
	v_add_u32_e32 v46, 16, v4
	v_mad_i64_i32 v[40:41], s[10:11], v46, s38, v[0:1]
	v_add_u32_e32 v46, 32, v4
	v_mad_i64_i32 v[42:43], s[10:11], v46, s38, v[0:1]
	v_add_u32_e32 v46, 48, v4
	v_mad_i64_i32 v[44:45], s[10:11], v46, s38, v[0:1]
	global_load_ushort v34, v[38:39], off
	global_load_ushort v35, v[40:41], off
	global_load_ushort v36, v[42:43], off
	global_load_ushort v37, v[44:45], off
	v_mov_b32_e32 v47, v2
	s_load_dwordx4 s[8:11], s[34:35], 0x48
	s_bfe_u32 s47, s14, 0x20005
	v_and_b32_e32 v14, 0x7f, v22
	s_lshl_b32 s18, s47, 7
	v_or_b32_e32 v0, s18, v14
	v_lshlrev_b32_e32 v8, 2, v0
	s_waitcnt lgkmcnt(0)
	v_lshl_add_u64 v[4:5], s[8:9], 0, v[8:9]
	v_add_co_u32_e32 v0, vcc, 0x1000, v4
	global_load_dword v15, v8, s[8:9] offset:2048
	s_nop 0
	v_addc_co_u32_e32 v1, vcc, 0, v5, vcc
	v_add_co_u32_e32 v2, vcc, 0x2000, v4
	v_bfe_u32 v23, v22, 7, 1
	s_nop 0
	v_addc_co_u32_e32 v3, vcc, 0, v5, vcc
	v_add_co_u32_e32 v6, vcc, 0x3000, v4
	v_lshl_add_u32 v22, v23, 11, s1
	s_nop 0
	v_addc_co_u32_e32 v7, vcc, 0, v5, vcc
	v_add_co_u32_e32 v10, vcc, 0x4000, v4
	s_nop 1
	v_addc_co_u32_e32 v11, vcc, 0, v5, vcc
	global_load_dword v16, v[0:1], off
	global_load_dword v17, v[0:1], off offset:2048
	global_load_dword v18, v[2:3], off
	global_load_dword v19, v[2:3], off offset:2048
	s_nop 0
	global_load_dword v0, v[6:7], off
	global_load_dword v1, v[6:7], off offset:2048
	global_load_dword v2, v[10:11], off
	global_load_dword v3, v[10:11], off offset:2048
	v_add_co_u32_e32 v6, vcc, 0x5000, v4
	s_nop 1
	v_addc_co_u32_e32 v7, vcc, 0, v5, vcc
	v_add_co_u32_e32 v10, vcc, 0x6000, v4
	s_nop 1
	v_addc_co_u32_e32 v11, vcc, 0, v5, vcc
	v_add_co_u32_e32 v24, vcc, 0x7000, v4
	s_nop 1
	v_addc_co_u32_e32 v25, vcc, 0, v5, vcc
	global_load_dword v21, v8, s[8:9]
	global_load_dword v4, v[6:7], off
	global_load_dword v5, v[6:7], off offset:2048
	s_nop 0
	global_load_dword v6, v[10:11], off
	global_load_dword v7, v[10:11], off offset:2048
	s_nop 0
	global_load_dword v10, v[24:25], off
	s_nop 0
	global_load_dword v8, v8, s[10:11]
	s_nop 0
	global_load_dword v11, v[24:25], off offset:2048
	v_lshlrev_b32_e32 v24, 2, v14
	v_lshl_or_b32 v23, v23, 14, v24
	s_mov_b32 s8, 0
	v_add_u32_e32 v23, s33, v23
	v_mov_b32_e32 v24, 0
	s_waitcnt vmcnt(17)
	v_lshlrev_b32_e32 v34, 16, v34
	v_lshlrev_b32_e32 v35, 16, v35
	v_lshlrev_b32_e32 v36, 16, v36
	v_lshlrev_b32_e32 v37, 16, v37
	ds_write_b32 v47, v34
	ds_write_b32 v47, v35 offset:1024
	ds_write_b32 v47, v36 offset:2048
	ds_write_b32 v47, v37 offset:3072
	s_waitcnt lgkmcnt(0)
	s_barrier
